# attn V phase: row sums via v_pk_add_f32 tree (17 instr instead of 32), p1 exps to aligned spare VGPRs
# speedup vs baseline: 1.0371x; 1.0061x over previous
; __device__ __forceinline__ void softmaxT(f32x16& p0, f32x16& p1, float& mref, f32x16& negm, float& l_reg, float& alpha, bf16x8& pa0, bf16x8& pa1, bf16x8& pa2, bf16x8& pa3) {
;     ...
;   for (int r = 0; r < 16; ++r) { p0[r] = __builtin_amdgcn_exp2f(p0[r]); p1[r] = __builtin_amdgcn_exp2f(p1[r]); }
;   { float s0 = p0[0] + p1[0], s1 = p0[1] + p1[1], s2 = p0[2] + p1[2], s3 = p0[3] + p1[3];
; #pragma unroll
;     for (int r = 4; r < 16; r += 4) { s0 += p0[r] + p1[r]; s1 += p0[r + 1] + p1[r + 1]; s2 += p0[r + 2] + p1[r + 2]; s3 += p0[r + 3] + p1[r + 3]; }
;     l_reg += (s0 + s1) + (s2 + s3); }
;     ...
;   PK4(p0, 0, pa0); PK4(p0, 8, pa1); PK4(p1, 0, pa2); PK4(p1, 8, pa3);
.LBB0_525:
	v_exp_f32_e32 v66, v66
	v_exp_f32_e32 v222, v50
	v_exp_f32_e32 v67, v67
	v_exp_f32_e32 v223, v51
	v_exp_f32_e32 v68, v68
	v_exp_f32_e32 v224, v52
	v_exp_f32_e32 v69, v69
	v_exp_f32_e32 v225, v53
	v_exp_f32_e32 v70, v70
	v_exp_f32_e32 v226, v54
	v_exp_f32_e32 v71, v71
	v_exp_f32_e32 v227, v55
	v_exp_f32_e32 v72, v72
	v_exp_f32_e32 v228, v56
	v_exp_f32_e32 v73, v73
	v_exp_f32_e32 v229, v57
	v_exp_f32_e32 v74, v74
	v_exp_f32_e32 v230, v58
	v_exp_f32_e32 v75, v75
	v_exp_f32_e32 v231, v59
	v_exp_f32_e32 v76, v76
	v_exp_f32_e32 v232, v60
	v_exp_f32_e32 v77, v77
	v_exp_f32_e32 v233, v61
	v_exp_f32_e32 v78, v78
	v_exp_f32_e32 v234, v62
	v_exp_f32_e32 v79, v79
	v_exp_f32_e32 v235, v63
	v_exp_f32_e32 v80, v80
	v_exp_f32_e32 v236, v64
	v_exp_f32_e32 v81, v81
	v_exp_f32_e32 v237, v65
	v_cvt_pk_bf16_f32 v54, v66, v67
	v_cvt_pk_bf16_f32 v55, v68, v69
	v_cvt_pk_bf16_f32 v56, v70, v71
	v_cvt_pk_bf16_f32 v57, v72, v73
	v_cvt_pk_bf16_f32 v50, v74, v75
	v_cvt_pk_bf16_f32 v51, v76, v77
	v_cvt_pk_bf16_f32 v52, v78, v79
	v_cvt_pk_bf16_f32 v53, v80, v81
	v_cvt_pk_bf16_f32 v58, v222, v223
	v_cvt_pk_bf16_f32 v59, v224, v225
	v_cvt_pk_bf16_f32 v60, v226, v227
	v_cvt_pk_bf16_f32 v61, v228, v229
	v_cvt_pk_bf16_f32 v62, v230, v231
	v_cvt_pk_bf16_f32 v63, v232, v233
	v_cvt_pk_bf16_f32 v64, v234, v235
	v_cvt_pk_bf16_f32 v65, v236, v237
	v_permlane32_swap_b32_e32 v54, v56
	v_permlane32_swap_b32_e32 v55, v57
	v_permlane32_swap_b32_e32 v50, v52
	v_permlane32_swap_b32_e32 v51, v53
	v_permlane32_swap_b32_e32 v58, v60
	v_permlane32_swap_b32_e32 v59, v61
	v_permlane32_swap_b32_e32 v62, v64
	v_permlane32_swap_b32_e32 v63, v65
	v_cmp_gt_f32_e32 vcc, 1.0, v158
	s_cbranch_vccz .LBB0_529
	s_and_saveexec_b64 s[0:1], s[2:3]
	ds_write_b32 v155, v158
	s_or_b64 exec, exec, s[0:1]
	s_waitcnt lgkmcnt(0)
	v_add_u32_e32 v158, v154, v132
	ds_read_b128 v[162:165], v158 offset:96
	ds_read_b128 v[166:169], v158 offset:64
	ds_read_b128 v[170:173], v158 offset:32
	ds_read_b128 v[192:195], v158
	s_waitcnt lgkmcnt(3)
	v_pk_mul_f32 v[46:47], v[46:47], v[162:163]
	s_waitcnt lgkmcnt(2)
	v_pk_mul_f32 v[42:43], v[42:43], v[166:167]
	s_waitcnt lgkmcnt(1)
	v_pk_mul_f32 v[38:39], v[38:39], v[170:171]
	v_pk_mul_f32 v[48:49], v[48:49], v[164:165]
	v_pk_mul_f32 v[44:45], v[44:45], v[168:169]
	v_pk_mul_f32 v[40:41], v[40:41], v[172:173]
	s_waitcnt lgkmcnt(0)
	v_pk_mul_f32 v[36:37], v[36:37], v[194:195]
	v_pk_mul_f32 v[34:35], v[34:35], v[192:193]
	v_pk_mul_f32 v[30:31], v[30:31], v[162:163]
	v_pk_mul_f32 v[26:27], v[26:27], v[166:167]
	v_pk_mul_f32 v[22:23], v[22:23], v[170:171]
	v_pk_mul_f32 v[32:33], v[32:33], v[164:165]
	v_pk_mul_f32 v[28:29], v[28:29], v[168:169]
	v_pk_mul_f32 v[24:25], v[24:25], v[172:173]
	v_pk_mul_f32 v[20:21], v[20:21], v[194:195]
	v_pk_mul_f32 v[18:19], v[18:19], v[192:193]

; __device__ __forceinline__ void softmaxT(f32x16& p0, f32x16& p1, float& mref, f32x16& negm, float& l_reg, float& alpha, bf16x8& pa0, bf16x8& pa1, bf16x8& pa2, bf16x8& pa3) {
;     ...
;   { float s0 = p0[0] + p1[0], s1 = p0[1] + p1[1], s2 = p0[2] + p1[2], s3 = p0[3] + p1[3];
; #pragma unroll
;     for (int r = 4; r < 16; r += 4) { s0 += p0[r] + p1[r]; s1 += p0[r + 1] + p1[r + 1]; s2 += p0[r + 2] + p1[r + 2]; s3 += p0[r + 3] + p1[r + 3]; }
;     l_reg += (s0 + s1) + (s2 + s3); }
; __device__ __forceinline__ void qkt(f32x16& p0, f32x16& p1, const LAS unsigned char* Ks, const bf16x8* qr, const f32x16& negm, int r32, int hi) {
;   bf16x8 kf[12];
; #pragma unroll
;   for (int d0 = 0; d0 < 6; ++d0) { const int cb = (d0 * 16 + hi * 8) * 2;
;     kf[2 * d0] = *(const LAS bf16x8*)(Ks + KSWZ(r32, cb)); kf[2 * d0 + 1] = *(const LAS bf16x8*)(Ks + KSWZ(32 + r32, cb)); }
;   SBAR();
;   p0 = __builtin_amdgcn_mfma_f32_32x32x16_bf16(kf[0], qr[0], negm, 0, 0, 0); p1 = __builtin_amdgcn_mfma_f32_32x32x16_bf16(kf[1], qr[0], negm, 0, 0, 0);
; #pragma unroll
;   for (int d0 = 1; d0 < 6; ++d0) { p0 = __builtin_amdgcn_mfma_f32_32x32x16_bf16(kf[2 * d0], qr[d0], p0, 0, 0, 0); p1 = __builtin_amdgcn_mfma_f32_32x32x16_bf16(kf[2 * d0 + 1], qr[d0], p1, 0, 0, 0); }
; }
; __device__ __forceinline__ int v_st(int k, int c) { const int kk = (k & ~0xC) | ((k & 4) << 1) | ((k & 8) >> 1); return ((kk >> 3) * 4 + (c >> 5)) * 512 + ((kk & 7) * 32 + (c & 31)) * 2; }
; __device__ __forceinline__ int v_rd_base(int lane) { return ((lane & 3) << 3) | (((lane >> 2) & 3) << 6) | (((lane >> 4) & 1) << 5) | (((lane >> 5) & 1) << 8); }
; template <int OFF> __device__ __forceinline__ s16x4 tr_read(int vb) {
;   s16x4 r; asm volatile("ds_read_b64_tr_b16 %0, %1 offset:%2" : "=&v"(r) : "v"(vb), "i"(OFF) : "memory"); return r;
; }
; __device__ __forceinline__ void pv_d0(f32x16* o, int vb, bf16x8 pa0, bf16x8 pa1, bf16x8 pa2, bf16x8 pa3) {
;   const s16x4 a0 = tr_read<v_rd_off(0, 0, 0)>(vb), b0 = tr_read<v_rd_off(0, 0, 1)>(vb), a1 = tr_read<v_rd_off(0, 1, 0)>(vb), b1 = tr_read<v_rd_off(0, 1, 1)>(vb);
;   const s16x4 a2 = tr_read<v_rd_off(0, 2, 0)>(vb), b2 = tr_read<v_rd_off(0, 2, 1)>(vb), a3 = tr_read<v_rd_off(0, 3, 0)>(vb), b3 = tr_read<v_rd_off(0, 3, 1)>(vb);
;   const s16x4 c0 = tr_read<v_rd_off(1, 0, 0)>(vb), d0 = tr_read<v_rd_off(1, 0, 1)>(vb), c1 = tr_read<v_rd_off(1, 1, 0)>(vb), d1 = tr_read<v_rd_off(1, 1, 1)>(vb);
.LBB0_531:
	v_pk_add_f32 v[222:223], v[66:67], v[222:223]
	v_pk_add_f32 v[224:225], v[68:69], v[224:225]
	v_pk_add_f32 v[226:227], v[70:71], v[226:227]
	v_pk_add_f32 v[228:229], v[72:73], v[228:229]
	v_pk_add_f32 v[230:231], v[74:75], v[230:231]
	v_pk_add_f32 v[232:233], v[76:77], v[232:233]
	v_pk_add_f32 v[234:235], v[78:79], v[234:235]
	v_pk_add_f32 v[236:237], v[80:81], v[236:237]
	v_pk_add_f32 v[222:223], v[222:223], v[224:225]
	v_pk_add_f32 v[226:227], v[226:227], v[228:229]
	v_pk_add_f32 v[230:231], v[230:231], v[232:233]
	v_pk_add_f32 v[234:235], v[234:235], v[236:237]
	v_pk_add_f32 v[222:223], v[222:223], v[226:227]
	v_pk_add_f32 v[230:231], v[230:231], v[234:235]
	v_pk_add_f32 v[222:223], v[222:223], v[230:231]
	v_add_f32_e32 v222, v222, v223
	v_add_f32_e32 v157, v157, v222
	v_add_u32_e32 v174, s5, v156
	ds_read_b64_tr_b16 v[66:67], v174 offset:0
	ds_read_b64_tr_b16 v[68:69], v174 offset:0x800
	ds_read_b64_tr_b16 v[158:159], v174 offset:0x200
	ds_read_b64_tr_b16 v[160:161], v174 offset:0xa00
	s_waitcnt lgkmcnt(4)
	s_barrier
	s_setprio 2
	ds_read_b64_tr_b16 v[70:71], v174 offset:0x1000
	ds_read_b64_tr_b16 v[72:73], v174 offset:0x1800
	ds_read_b64_tr_b16 v[162:163], v174 offset:0x1200
	ds_read_b64_tr_b16 v[164:165], v174 offset:0x1a00
	ds_read_b64_tr_b16 v[74:75], v174 offset:0x2000
	ds_read_b64_tr_b16 v[76:77], v174 offset:0x2800
	ds_read_b64_tr_b16 v[166:167], v174 offset:0x2200
	ds_read_b64_tr_b16 v[168:169], v174 offset:0x2a00
	ds_read_b64_tr_b16 v[78:79], v174 offset:0x3000
	ds_read_b64_tr_b16 v[80:81], v174 offset:0x3800
	ds_read_b64_tr_b16 v[170:171], v174 offset:0x3200
	ds_read_b64_tr_b16 v[172:173], v174 offset:0x3a00
	s_waitcnt lgkmcnt(14)
	v_mfma_f32_32x32x16_bf16 v[34:49], v[54:57], v[66:69], v[34:49]
	s_waitcnt lgkmcnt(12)
	v_mfma_f32_32x32x16_bf16 v[18:33], v[54:57], v[158:161], v[18:33]
	v_add_u32_e32 v54, s10, v146
	v_add_u32_e32 v55, v54, v147
	s_waitcnt lgkmcnt(10)
	v_mfma_f32_32x32x16_bf16 v[34:49], v[50:53], v[70:73], v[34:49]
	s_waitcnt lgkmcnt(8)
	v_mfma_f32_32x32x16_bf16 v[18:33], v[50:53], v[162:165], v[18:33]
	ds_read_b128 v[50:53], v55 offset:49152
	ds_read_b128 v[158:161], v55 offset:57344
	v_add_u32_e32 v55, v54, v148
	s_waitcnt lgkmcnt(8)
	v_mfma_f32_32x32x16_bf16 v[34:49], v[58:61], v[74:77], v[34:49]
	s_waitcnt lgkmcnt(6)
	v_mfma_f32_32x32x16_bf16 v[18:33], v[58:61], v[166:169], v[18:33]
	ds_read_b128 v[162:165], v55 offset:49152
	ds_read_b128 v[166:169], v55 offset:57344
	v_add_u32_e32 v55, v54, v149
	s_waitcnt lgkmcnt(6)
	v_mfma_f32_32x32x16_bf16 v[34:49], v[62:65], v[78:81], v[34:49]
	s_waitcnt lgkmcnt(4)
	v_mfma_f32_32x32x16_bf16 v[18:33], v[62:65], v[170:173], v[18:33]
	ds_read_b128 v[170:173], v55 offset:49152
	ds_read_b128 v[178:181], v55 offset:57344
	v_add_u32_e32 v55, v54, v150
	ds_read_b128 v[182:185], v55 offset:49152
	ds_read_b128 v[186:189], v55 offset:57344
	v_add_u32_e32 v55, v54, v151
	v_add_u32_e32 v54, v54, v152
	ds_read_b128 v[190:193], v55 offset:49152
	ds_read_b128 v[194:197], v55 offset:57344
	ds_read_b128 v[198:201], v54 offset:49152
	ds_read_b128 v[202:205], v54 offset:57344
	s_waitcnt lgkmcnt(11)
	v_mfma_f32_32x32x16_bf16 v[66:81], v[50:53], v[82:85], v[2:17]
	s_waitcnt lgkmcnt(9)
	v_mfma_f32_32x32x16_bf16 v[66:81], v[162:165], v[86:89], v[66:81]
	s_waitcnt lgkmcnt(7)
	v_mfma_f32_32x32x16_bf16 v[66:81], v[170:173], v[90:93], v[66:81]
	s_waitcnt lgkmcnt(5)
	v_mfma_f32_32x32x16_bf16 v[66:81], v[182:185], v[94:97], v[66:81]
	s_waitcnt lgkmcnt(3)
	v_mfma_f32_32x32x16_bf16 v[66:81], v[190:193], v[98:101], v[66:81]
	s_waitcnt lgkmcnt(1)
	v_mfma_f32_32x32x16_bf16 v[66:81], v[198:201], v[102:105], v[66:81]
	s_waitcnt lgkmcnt(0)
	v_mfma_f32_32x32x16_bf16 v[50:65], v[158:161], v[82:85], v[2:17]
	v_mfma_f32_32x32x16_bf16 v[50:65], v[166:169], v[86:89], v[50:65]
	v_mfma_f32_32x32x16_bf16 v[50:65], v[178:181], v[90:93], v[50:65]
	v_mfma_f32_32x32x16_bf16 v[50:65], v[186:189], v[94:97], v[50:65]
	v_mfma_f32_32x32x16_bf16 v[50:65], v[194:197], v[98:101], v[50:65]
	v_mfma_f32_32x32x16_bf16 v[50:65], v[202:205], v[102:105], v[50:65]
	s_setprio 0
	v_max3_f32 v158, v66, v67, v68
	v_max3_f32 v159, v69, v70, v71
	v_max3_f32 v158, v158, v72, v73
	v_max3_f32 v159, v159, v74, v75
	v_max3_f32 v158, v158, v76, v77
	v_max3_f32 v159, v159, v78, v79
	v_max3_f32 v158, v158, v80, v81
	s_nop 3
	v_max3_f32 v159, v159, v50, v51
	v_max3_f32 v158, v158, v52, v53
	v_max3_f32 v159, v159, v54, v55
	v_max3_f32 v158, v158, v56, v57
	v_max3_f32 v159, v159, v58, v59
	v_max3_f32 v158, v158, v60, v61
	v_max3_f32 v159, v159, v62, v63
	v_max3_f32 v158, v158, v64, v65
	v_max_f32_e32 v158, v158, v159
	v_mov_b32_e32 v159, v158
	s_nop 1
	v_permlane32_swap_b32_e32 v158, v159
	v_max_f32_e32 v159, v158, v159
	v_cmp_ge_f32_e32 vcc, s93, v159
	s_cmp_eq_u64 vcc, exec
	v_mov_b32_e32 v158, 1.0
	s_barrier
	s_cbranch_scc0 .LBB0_541
; __device__ __forceinline__ void softmaxT(f32x16& p0, f32x16& p1, float& mref, f32x16& negm, float& l_reg, float& alpha, bf16x8& pa0, bf16x8& pa1, bf16x8& pa2, bf16x8& pa3) {
;     ...
;   for (int r = 0; r < 16; ++r) { p0[r] = __builtin_amdgcn_exp2f(p0[r]); p1[r] = __builtin_amdgcn_exp2f(p1[r]); }
;   { float s0 = p0[0] + p1[0], s1 = p0[1] + p1[1], s2 = p0[2] + p1[2], s3 = p0[3] + p1[3];
; #pragma unroll
;     for (int r = 4; r < 16; r += 4) { s0 += p0[r] + p1[r]; s1 += p0[r + 1] + p1[r + 1]; s2 += p0[r + 2] + p1[r + 2]; s3 += p0[r + 3] + p1[r + 3]; }
;     l_reg += (s0 + s1) + (s2 + s3); }
;     ...
;   PK4(p0, 0, pa0); PK4(p0, 8, pa1); PK4(p1, 0, pa2); PK4(p1, 8, pa3);
.LBB0_532:
	v_exp_f32_e32 v66, v66
	v_exp_f32_e32 v222, v50
	v_exp_f32_e32 v67, v67
	v_exp_f32_e32 v223, v51
	v_exp_f32_e32 v68, v68
	v_exp_f32_e32 v224, v52
	v_exp_f32_e32 v69, v69
	v_exp_f32_e32 v225, v53
	v_exp_f32_e32 v70, v70
	v_exp_f32_e32 v226, v54
	v_exp_f32_e32 v71, v71
	v_exp_f32_e32 v227, v55
	v_exp_f32_e32 v72, v72
	v_exp_f32_e32 v228, v56
	v_exp_f32_e32 v73, v73
	v_exp_f32_e32 v229, v57
	v_exp_f32_e32 v74, v74
	v_exp_f32_e32 v230, v58
	v_exp_f32_e32 v75, v75
	v_exp_f32_e32 v231, v59
	v_exp_f32_e32 v76, v76
	v_exp_f32_e32 v232, v60
	v_exp_f32_e32 v77, v77
	v_exp_f32_e32 v233, v61
	v_exp_f32_e32 v78, v78
	v_exp_f32_e32 v234, v62
	v_exp_f32_e32 v79, v79
	v_exp_f32_e32 v235, v63
	v_exp_f32_e32 v80, v80
	v_exp_f32_e32 v236, v64
	v_exp_f32_e32 v81, v81
	v_exp_f32_e32 v237, v65
	v_cvt_pk_bf16_f32 v62, v66, v67
	v_cvt_pk_bf16_f32 v63, v68, v69
	v_cvt_pk_bf16_f32 v64, v70, v71
	v_cvt_pk_bf16_f32 v65, v72, v73
	v_cvt_pk_bf16_f32 v50, v74, v75
	v_cvt_pk_bf16_f32 v51, v76, v77
	v_cvt_pk_bf16_f32 v52, v78, v79
	v_cvt_pk_bf16_f32 v53, v80, v81
	v_cvt_pk_bf16_f32 v54, v222, v223
	v_cvt_pk_bf16_f32 v55, v224, v225
	v_cvt_pk_bf16_f32 v56, v226, v227
	v_cvt_pk_bf16_f32 v57, v228, v229
	v_cvt_pk_bf16_f32 v58, v230, v231
	v_cvt_pk_bf16_f32 v59, v232, v233
	v_cvt_pk_bf16_f32 v60, v234, v235
	v_cvt_pk_bf16_f32 v61, v236, v237
	v_permlane32_swap_b32_e32 v62, v64
	v_permlane32_swap_b32_e32 v63, v65
	v_permlane32_swap_b32_e32 v50, v52
	v_permlane32_swap_b32_e32 v51, v53
	v_permlane32_swap_b32_e32 v54, v56
	v_permlane32_swap_b32_e32 v55, v57
	v_permlane32_swap_b32_e32 v58, v60
	v_permlane32_swap_b32_e32 v59, v61
	v_cmp_gt_f32_e32 vcc, 1.0, v158
	s_cbranch_vccz .LBB0_536
	s_and_saveexec_b64 s[0:1], s[2:3]
	ds_write_b32 v155, v158
	s_or_b64 exec, exec, s[0:1]
	s_waitcnt lgkmcnt(0)
	v_add_u32_e32 v158, v154, v132
	ds_read_b128 v[162:165], v158 offset:96
	ds_read_b128 v[166:169], v158 offset:64
	ds_read_b128 v[170:173], v158 offset:32
	ds_read_b128 v[192:195], v158
	s_waitcnt lgkmcnt(3)
	v_pk_mul_f32 v[46:47], v[46:47], v[162:163]
	s_waitcnt lgkmcnt(2)
	v_pk_mul_f32 v[42:43], v[42:43], v[166:167]
	s_waitcnt lgkmcnt(1)
	v_pk_mul_f32 v[38:39], v[38:39], v[170:171]
	v_pk_mul_f32 v[48:49], v[48:49], v[164:165]
	v_pk_mul_f32 v[44:45], v[44:45], v[168:169]
	v_pk_mul_f32 v[40:41], v[40:41], v[172:173]
	s_waitcnt lgkmcnt(0)
	v_pk_mul_f32 v[36:37], v[36:37], v[194:195]
	v_pk_mul_f32 v[34:35], v[34:35], v[192:193]
	v_pk_mul_f32 v[30:31], v[30:31], v[162:163]
	v_pk_mul_f32 v[26:27], v[26:27], v[166:167]
	v_pk_mul_f32 v[22:23], v[22:23], v[170:171]
	v_pk_mul_f32 v[32:33], v[32:33], v[164:165]
	v_pk_mul_f32 v[28:29], v[28:29], v[168:169]
	v_pk_mul_f32 v[24:25], v[24:25], v[172:173]
	v_pk_mul_f32 v[20:21], v[20:21], v[194:195]
	v_pk_mul_f32 v[18:19], v[18:19], v[192:193]

; #define PHASE_M(j) do { SBAR(); __builtin_amdgcn_s_setprio(2); if ((j) > 0) pv_d0(o, vb0 + bV, pa0, pa1, pa2, pa3); qkt(p0, p1, Kb + bK, qr, negm, r32, hi); __builtin_amdgcn_s_setprio(0); SBAR(); __syncthreads(); } while (0)
; #define PHASE_V(j, slot) do { softmaxT(p0, p1, mref, negm, l_reg, alpha, pa0, pa1, pa2, pa3); RESC(alpha); \
;     { const int s_ = (j) + 1 + trail; if (s_ < NT) { asm volatile("s_waitcnt vmcnt(3)" ::: "memory"); SWRITE_AT(trail ? bNN : bN, slot); const int s2_ = s_ + 2; SLOAD(slot, s2_ < NT ? s2_ : NT - 1); } } \
;     __syncthreads(); bV = bK; bK = bN; bN = bNN; bNN = bV; } while (0)
; __device__ __forceinline__ void softmaxT(f32x16& p0, f32x16& p1, float& mref, f32x16& negm, float& l_reg, float& alpha, bf16x8& pa0, bf16x8& pa1, bf16x8& pa2, bf16x8& pa3) {
;     ...
;   { float s0 = p0[0] + p1[0], s1 = p0[1] + p1[1], s2 = p0[2] + p1[2], s3 = p0[3] + p1[3];
; #pragma unroll
;     for (int r = 4; r < 16; r += 4) { s0 += p0[r] + p1[r]; s1 += p0[r + 1] + p1[r + 1]; s2 += p0[r + 2] + p1[r + 2]; s3 += p0[r + 3] + p1[r + 3]; }
;     l_reg += (s0 + s1) + (s2 + s3); }
; __device__ __forceinline__ void attn_unit(const bf16_t* __restrict__ Qb, bool rope_q, int tq0, const bf16_t* __restrict__ KVh, const bf16_t* __restrict__ KR,
;                                           int ctx_row0, int lat_row0, int NT, bf16_t* __restrict__ Ob, LAS unsigned char* lds, int wave_s) {
;     ...
;   for (int j = 0; j < NT; j += 2) {
;     PHASE_M(j); PHASE_V(j, 1);
;     PHASE_M(j + 1); PHASE_V(j + 1, 0);
;   }
.LBB0_538:
	v_pk_add_f32 v[222:223], v[66:67], v[222:223]
	v_pk_add_f32 v[224:225], v[68:69], v[224:225]
	v_pk_add_f32 v[226:227], v[70:71], v[226:227]
	v_pk_add_f32 v[228:229], v[72:73], v[228:229]
	v_pk_add_f32 v[230:231], v[74:75], v[230:231]
	v_pk_add_f32 v[232:233], v[76:77], v[232:233]
	v_pk_add_f32 v[234:235], v[78:79], v[234:235]
	v_pk_add_f32 v[236:237], v[80:81], v[236:237]
	v_pk_add_f32 v[222:223], v[222:223], v[224:225]
	v_pk_add_f32 v[226:227], v[226:227], v[228:229]
	v_pk_add_f32 v[230:231], v[230:231], v[232:233]
	v_pk_add_f32 v[234:235], v[234:235], v[236:237]
	v_pk_add_f32 v[222:223], v[222:223], v[226:227]
	v_pk_add_f32 v[230:231], v[230:231], v[234:235]
	v_pk_add_f32 v[222:223], v[222:223], v[230:231]
	v_add_f32_e32 v222, v222, v223
	s_add_i32 s11, s11, 2
	v_add_f32_e32 v157, v157, v222
	s_and_b64 vcc, exec, s[0:1]
	v_add_u32_e32 v174, s10, v156
	ds_read_b64_tr_b16 v[66:67], v174 offset:0
	ds_read_b64_tr_b16 v[68:69], v174 offset:0x800
	ds_read_b64_tr_b16 v[158:159], v174 offset:0x200
	ds_read_b64_tr_b16 v[160:161], v174 offset:0xa00
	s_waitcnt lgkmcnt(4)
	s_barrier
	s_cbranch_vccnz .LBB0_542
	s_mov_b32 s0, s10
	s_mov_b32 s10, s5
	s_mov_b32 s5, s22
	s_mov_b32 s22, s0
	s_setprio 2
	s_branch .Lmy_attn_m1
